# grid barrier: every XCD leader releases all XCDs directly after its L2 writeback (16 no-return adds on the per-XCD generation words); waiters spin until their word reaches nx*gen+1; the cross-XCD arri
# speedup vs baseline: 1.0058x; 1.0058x over previous
.LBB0_247:
	v_readlane_b32 s4, v251, 23
	v_readlane_b32 s5, v251, 24
	s_lshl_b64 s[4:5], s[4:5], 2
	s_add_u32 s38, s2, s4
	s_addc_u32 s28, s3, s5
	v_mov_b32_e32 v3, s38
	v_add_co_u32_e32 v6, vcc, 0x1000, v3
	v_mov_b32_e32 v3, s28
	s_nop 0
	v_addc_co_u32_e32 v7, vcc, 0, v3, vcc
	flat_atomic_add v5, v[6:7], v207 offset:1024 sc0
	v_cvt_f32_u32_e32 v3, v4
	v_sub_u32_e32 v6, 0, v4
	v_rcp_iflag_f32_e32 v3, v3
	s_nop 0
	v_mul_f32_e32 v3, 0x4f7ffffe, v3
	v_cvt_u32_f32_e32 v3, v3
	v_mul_lo_u32 v6, v6, v3
	v_mul_hi_u32 v6, v3, v6
	v_add_u32_e32 v3, v3, v6
	s_waitcnt vmcnt(0) lgkmcnt(0)
	buffer_inv sc1
	v_mul_hi_u32 v3, v5, v3
	v_mul_lo_u32 v6, v3, v4
	v_sub_u32_e32 v6, v5, v6
	v_cmp_ge_u32_e32 vcc, v6, v4
	v_add_u32_e32 v7, 1, v3
	s_nop 0
	v_cndmask_b32_e32 v3, v3, v7, vcc
	v_sub_u32_e32 v7, v6, v4
	v_cndmask_b32_e32 v6, v6, v7, vcc
	v_cmp_ge_u32_e32 vcc, v6, v4
	v_add_u32_e32 v6, 1, v3
	s_nop 0
	v_cndmask_b32_e32 v3, v3, v6, vcc
	v_add_u32_e32 v6, 1, v5
	v_mad_u64_u32 v[4:5], s[4:5], v4, v3, v[4:5]
	v_cmp_ne_u32_e32 vcc, v6, v4
	v_mad_u32_u24 v3, v3, v2, 1
	s_cbranch_vccnz .Lxb_nl_0
	buffer_wbl2 sc1
	s_waitcnt vmcnt(0)
	v_mov_b32_e32 v6, s2
	v_mov_b32_e32 v7, s3
	v_add_co_u32_e32 v6, vcc, 0x2400, v6
	s_nop 1
	v_addc_co_u32_e32 v7, vcc, 0, v7, vcc
	flat_atomic_add v[6:7], v207
	flat_atomic_add v[6:7], v207 offset:256
	flat_atomic_add v[6:7], v207 offset:512
	flat_atomic_add v[6:7], v207 offset:768
	flat_atomic_add v[6:7], v207 offset:1024
	flat_atomic_add v[6:7], v207 offset:1280
	flat_atomic_add v[6:7], v207 offset:1536
	flat_atomic_add v[6:7], v207 offset:1792
	flat_atomic_add v[6:7], v207 offset:2048
	flat_atomic_add v[6:7], v207 offset:2304
	flat_atomic_add v[6:7], v207 offset:2560
	flat_atomic_add v[6:7], v207 offset:2816
	flat_atomic_add v[6:7], v207 offset:3072
	flat_atomic_add v[6:7], v207 offset:3328
	flat_atomic_add v[6:7], v207 offset:3584
	flat_atomic_add v[6:7], v207 offset:3840
	s_mov_b64 vcc, exec
.Lxb_nl_0:
	s_and_saveexec_b64 s[4:5], vcc
	s_xor_b64 s[4:5], exec, s[4:5]
	s_cbranch_execz .LBB0_260
	v_mov_b32_e32 v2, s38
	v_add_co_u32_e32 v4, vcc, 0x2000, v2
	v_mov_b32_e32 v2, s28
	s_nop 0
	v_addc_co_u32_e32 v5, vcc, 0, v2, vcc
	flat_load_dword v2, v[4:5] offset:1024 sc1
	s_add_u32 s10, s38, 0x2400
	s_addc_u32 s11, s28, 0
	s_waitcnt vmcnt(0) lgkmcnt(0)
	v_cmp_lt_u32_e32 vcc, v2, v3
	s_and_saveexec_b64 s[8:9], vcc
	s_cbranch_execz .LBB0_259
	s_mov_b32 s39, 1
	s_mov_b64 s[12:13], 0
	s_branch .LBB0_251

.LBB0_255:
	s_andn2_b64 s[16:17], s[16:17], exec
	s_and_b64 s[22:23], s[22:23], exec
	s_or_b64 s[16:17], s[16:17], s[22:23]
	s_and_saveexec_b64 s[22:23], s[20:21]
	s_cbranch_execz .LBB0_250
	v_mov_b64_e32 v[4:5], s[10:11]
	flat_load_dword v2, v[4:5] sc1
	s_add_i32 s39, s39, 1
	s_or_b64 s[16:17], s[16:17], exec
	s_waitcnt vmcnt(0) lgkmcnt(0)
	v_cmp_ge_u32_e32 vcc, v2, v3
	s_orn2_b64 s[18:19], vcc, exec
	s_branch .LBB0_250

.LBB0_1364:
	v_readlane_b32 s4, v251, 23
	v_readlane_b32 s5, v251, 24
	s_lshl_b64 s[4:5], s[4:5], 2
	s_add_u32 s36, s2, s4
	s_addc_u32 s28, s3, s5
	v_mov_b32_e32 v3, s36
	v_add_co_u32_e32 v6, vcc, 0x1000, v3
	v_mov_b32_e32 v3, s28
	s_nop 0
	v_addc_co_u32_e32 v7, vcc, 0, v3, vcc
	flat_atomic_add v5, v[6:7], v207 offset:1024 sc0
	v_cvt_f32_u32_e32 v3, v4
	v_sub_u32_e32 v6, 0, v4
	v_rcp_iflag_f32_e32 v3, v3
	s_nop 0
	v_mul_f32_e32 v3, 0x4f7ffffe, v3
	v_cvt_u32_f32_e32 v3, v3
	v_mul_lo_u32 v6, v6, v3
	v_mul_hi_u32 v6, v3, v6
	v_add_u32_e32 v3, v3, v6
	s_waitcnt vmcnt(0) lgkmcnt(0)
	buffer_inv sc1
	v_mul_hi_u32 v3, v5, v3
	v_mul_lo_u32 v6, v3, v4
	v_sub_u32_e32 v6, v5, v6
	v_cmp_ge_u32_e32 vcc, v6, v4
	v_add_u32_e32 v7, 1, v3
	s_nop 0
	v_cndmask_b32_e32 v3, v3, v7, vcc
	v_sub_u32_e32 v7, v6, v4
	v_cndmask_b32_e32 v6, v6, v7, vcc
	v_cmp_ge_u32_e32 vcc, v6, v4
	v_add_u32_e32 v6, 1, v3
	s_nop 0
	v_cndmask_b32_e32 v3, v3, v6, vcc
	v_add_u32_e32 v6, 1, v5
	v_mad_u64_u32 v[4:5], s[4:5], v4, v3, v[4:5]
	v_cmp_ne_u32_e32 vcc, v6, v4
	v_mad_u32_u24 v3, v3, v2, 1
	s_cbranch_vccnz .Lxb_nl_3
	buffer_wbl2 sc1
	s_waitcnt vmcnt(0)
	v_mov_b32_e32 v6, s2
	v_mov_b32_e32 v7, s3
	v_add_co_u32_e32 v6, vcc, 0x2400, v6
	s_nop 1
	v_addc_co_u32_e32 v7, vcc, 0, v7, vcc
	flat_atomic_add v[6:7], v207
	flat_atomic_add v[6:7], v207 offset:256
	flat_atomic_add v[6:7], v207 offset:512
	flat_atomic_add v[6:7], v207 offset:768
	flat_atomic_add v[6:7], v207 offset:1024
	flat_atomic_add v[6:7], v207 offset:1280
	flat_atomic_add v[6:7], v207 offset:1536
	flat_atomic_add v[6:7], v207 offset:1792
	flat_atomic_add v[6:7], v207 offset:2048
	flat_atomic_add v[6:7], v207 offset:2304
	flat_atomic_add v[6:7], v207 offset:2560
	flat_atomic_add v[6:7], v207 offset:2816
	flat_atomic_add v[6:7], v207 offset:3072
	flat_atomic_add v[6:7], v207 offset:3328
	flat_atomic_add v[6:7], v207 offset:3584
	flat_atomic_add v[6:7], v207 offset:3840
	s_mov_b64 vcc, exec
.Lxb_nl_3:
	s_and_saveexec_b64 s[4:5], vcc
	s_xor_b64 s[4:5], exec, s[4:5]
	s_cbranch_execz .LBB0_1377
	v_mov_b32_e32 v2, s36
	v_add_co_u32_e32 v4, vcc, 0x2000, v2
	v_mov_b32_e32 v2, s28
	s_nop 0
	v_addc_co_u32_e32 v5, vcc, 0, v2, vcc
	flat_load_dword v2, v[4:5] offset:1024 sc1
	s_add_u32 s8, s36, 0x2400
	s_addc_u32 s9, s28, 0
	s_waitcnt vmcnt(0) lgkmcnt(0)
	v_cmp_lt_u32_e32 vcc, v2, v3
	s_and_saveexec_b64 s[6:7], vcc
	s_cbranch_execz .LBB0_1376
	s_mov_b32 s37, 1
	s_mov_b64 s[10:11], 0
	s_branch .LBB0_1368

.LBB0_1372:
	s_andn2_b64 s[14:15], s[14:15], exec
	s_and_b64 s[20:21], s[20:21], exec
	s_or_b64 s[14:15], s[14:15], s[20:21]
	s_and_saveexec_b64 s[20:21], s[18:19]
	s_cbranch_execz .LBB0_1367
	v_mov_b64_e32 v[4:5], s[8:9]
	flat_load_dword v2, v[4:5] sc1
	s_add_i32 s37, s37, 1
	s_or_b64 s[14:15], s[14:15], exec
	s_waitcnt vmcnt(0) lgkmcnt(0)
	v_cmp_ge_u32_e32 vcc, v2, v3
	s_orn2_b64 s[16:17], vcc, exec
	s_branch .LBB0_1367

.Lxb_nl_5:
	s_and_saveexec_b64 s[4:5], vcc
	s_xor_b64 s[4:5], exec, s[4:5]
	s_cbranch_execz .LBB0_1536
	v_mov_b32_e32 v2, s38
	v_add_co_u32_e32 v4, vcc, 0x2000, v2
	v_mov_b32_e32 v2, s28
	s_nop 0
	v_addc_co_u32_e32 v5, vcc, 0, v2, vcc
	flat_load_dword v2, v[4:5] offset:1024 sc1
	s_add_u32 s8, s38, 0x2400
	s_addc_u32 s9, s28, 0
	s_waitcnt vmcnt(0) lgkmcnt(0)
	v_cmp_lt_u32_e32 vcc, v2, v3
	s_and_saveexec_b64 s[6:7], vcc
	s_cbranch_execz .LBB0_1535
	s_mov_b32 s39, 1
	s_mov_b64 s[10:11], 0
	s_branch .LBB0_1527

.LBB0_1531:
	s_andn2_b64 s[14:15], s[14:15], exec
	s_and_b64 s[20:21], s[20:21], exec
	s_or_b64 s[14:15], s[14:15], s[20:21]
	s_and_saveexec_b64 s[20:21], s[18:19]
	s_cbranch_execz .LBB0_1526
	v_mov_b64_e32 v[4:5], s[8:9]
	flat_load_dword v2, v[4:5] sc1
	s_add_i32 s39, s39, 1
	s_or_b64 s[14:15], s[14:15], exec
	s_waitcnt vmcnt(0) lgkmcnt(0)
	v_cmp_ge_u32_e32 vcc, v2, v3
	s_orn2_b64 s[16:17], vcc, exec
	s_branch .LBB0_1526

.LBB0_1795:
	v_readlane_b32 s4, v251, 23
	v_readlane_b32 s5, v251, 24
	s_lshl_b64 s[4:5], s[4:5], 2
	s_add_u32 s28, s2, s4
	s_addc_u32 s25, s3, s5
	v_mov_b32_e32 v3, s28
	v_add_co_u32_e32 v6, vcc, 0x1000, v3
	v_mov_b32_e32 v3, s25
	s_nop 0
	v_addc_co_u32_e32 v7, vcc, 0, v3, vcc
	flat_atomic_add v5, v[6:7], v207 offset:1024 sc0
	v_cvt_f32_u32_e32 v3, v4
	v_sub_u32_e32 v6, 0, v4
	v_rcp_iflag_f32_e32 v3, v3
	s_nop 0
	v_mul_f32_e32 v3, 0x4f7ffffe, v3
	v_cvt_u32_f32_e32 v3, v3
	v_mul_lo_u32 v6, v6, v3
	v_mul_hi_u32 v6, v3, v6
	v_add_u32_e32 v3, v3, v6
	s_waitcnt vmcnt(0) lgkmcnt(0)
	buffer_inv sc1
	v_mul_hi_u32 v3, v5, v3
	v_mul_lo_u32 v6, v3, v4
	v_sub_u32_e32 v6, v5, v6
	v_cmp_ge_u32_e32 vcc, v6, v4
	v_add_u32_e32 v7, 1, v3
	s_nop 0
	v_cndmask_b32_e32 v3, v3, v7, vcc
	v_sub_u32_e32 v7, v6, v4
	v_cndmask_b32_e32 v6, v6, v7, vcc
	v_cmp_ge_u32_e32 vcc, v6, v4
	v_add_u32_e32 v6, 1, v3
	s_nop 0
	v_cndmask_b32_e32 v3, v3, v6, vcc
	v_add_u32_e32 v6, 1, v5
	v_mad_u64_u32 v[4:5], s[4:5], v4, v3, v[4:5]
	v_cmp_ne_u32_e32 vcc, v6, v4
	v_mad_u32_u24 v3, v3, v2, 1
	s_cbranch_vccnz .Lxb_nl_8
	buffer_wbl2 sc1
	s_waitcnt vmcnt(0)
	v_mov_b32_e32 v6, s2
	v_mov_b32_e32 v7, s3
	v_add_co_u32_e32 v6, vcc, 0x2400, v6
	s_nop 1
	v_addc_co_u32_e32 v7, vcc, 0, v7, vcc
	flat_atomic_add v[6:7], v207
	flat_atomic_add v[6:7], v207 offset:256
	flat_atomic_add v[6:7], v207 offset:512
	flat_atomic_add v[6:7], v207 offset:768
	flat_atomic_add v[6:7], v207 offset:1024
	flat_atomic_add v[6:7], v207 offset:1280
	flat_atomic_add v[6:7], v207 offset:1536
	flat_atomic_add v[6:7], v207 offset:1792
	flat_atomic_add v[6:7], v207 offset:2048
	flat_atomic_add v[6:7], v207 offset:2304
	flat_atomic_add v[6:7], v207 offset:2560
	flat_atomic_add v[6:7], v207 offset:2816
	flat_atomic_add v[6:7], v207 offset:3072
	flat_atomic_add v[6:7], v207 offset:3328
	flat_atomic_add v[6:7], v207 offset:3584
	flat_atomic_add v[6:7], v207 offset:3840
	s_mov_b64 vcc, exec
.Lxb_nl_8:
	s_and_saveexec_b64 s[4:5], vcc
	s_xor_b64 s[4:5], exec, s[4:5]
	s_cbranch_execz .LBB0_1808
	v_mov_b32_e32 v2, s28
	v_add_co_u32_e32 v4, vcc, 0x2000, v2
	v_mov_b32_e32 v2, s25
	s_nop 0
	v_addc_co_u32_e32 v5, vcc, 0, v2, vcc
	flat_load_dword v2, v[4:5] offset:1024 sc1
	s_add_u32 s8, s28, 0x2400
	s_addc_u32 s9, s25, 0
	s_waitcnt vmcnt(0) lgkmcnt(0)
	v_cmp_lt_u32_e32 vcc, v2, v3
	s_and_saveexec_b64 s[6:7], vcc
	s_cbranch_execz .LBB0_1807
	s_mov_b32 s36, 1
	s_mov_b64 s[10:11], 0
	s_branch .LBB0_1799

.LBB0_1803:
	s_andn2_b64 s[14:15], s[14:15], exec
	s_and_b64 s[20:21], s[20:21], exec
	s_or_b64 s[14:15], s[14:15], s[20:21]
	s_and_saveexec_b64 s[20:21], s[18:19]
	s_cbranch_execz .LBB0_1798
	v_mov_b64_e32 v[4:5], s[8:9]
	flat_load_dword v2, v[4:5] sc1
	s_add_i32 s36, s36, 1
	s_or_b64 s[14:15], s[14:15], exec
	s_waitcnt vmcnt(0) lgkmcnt(0)
	v_cmp_ge_u32_e32 vcc, v2, v3
	s_orn2_b64 s[16:17], vcc, exec
	s_branch .LBB0_1798
